# 12c: residual row (out) load of each token issued at the top of its half-iteration instead of ~90 instructions before use
# speedup vs baseline: 1.0032x; 1.0032x over previous
; DI void peer_v_phase(const Params& p) {
;     ...
;   auto gather = [&](PeerVRows& r, const int* e, int tok) {
; #pragma unroll
;     for (int i = 0; i < 16; ++i) r.v[i] = *(const u32x4*)(Vb + (size_t)e[i] * 128);
;     const float4* wp = (const float4*)(W + (size_t)tok * 128 + 16 * q);
; #pragma unroll
;     for (int j = 0; j < 4; ++j) r.w[j] = wp[j];
;   };
;   auto compute = [&](const PeerVRows& r, int tok) {
;     f32x2 o2[8];
; #pragma unroll
;     for (int k = 0; k < 8; ++k) { o2[k][0] = 0.f; o2[k][1] = 0.f; }
; #pragma unroll
;     for (int i = 0; i < 16; ++i) {
;       const float wi = (i & 3) == 0 ? r.w[i >> 2].x : (i & 3) == 1 ? r.w[i >> 2].y : (i & 3) == 2 ? r.w[i >> 2].z : r.w[i >> 2].w;
;       const f32x2 w2 = {wi, wi};
; #pragma unroll
;       for (int j = 0; j < 4; ++j) {
;         const f32x2 lo = __builtin_amdgcn_cvt_pk_f32_fp8((int)r.v[i][j], false);
;         const f32x2 hi = __builtin_amdgcn_cvt_pk_f32_fp8((int)r.v[i][j], true);
;         o2[2 * j] = __builtin_elementwise_fma(lo, w2, o2[2 * j]);
;         o2[2 * j + 1] = __builtin_elementwise_fma(hi, w2, o2[2 * j + 1]);
;       }
;     }
;     ...
;     float* xr = p.out + (size_t)tok * 1024 + 128 * g + 16 * s + 2 * q;
;     float2 y = *(const float2*)xr;
;     y.x += r2[0]; y.y += r2[1];
;     *(float2*)xr = y;
;     const float ss = wave_sum(y.x * y.x + y.y * y.y);
;     if (lane == 0) SSP[tok] = ss;
;   };
;   int ea[16], eb[16];
;   PeerVRows ga, gb;
;   peer_load_e(ea, EID, tokof(0), q);
;   peer_load_e(eb, EID, tokof(1), q);
;   gather(ga, ea, tokof(0));
;   for (int k = 0; k < n; k += 2) {
;     peer_load_e(ea, EID, tokof(k + 2), q);
;     gather(gb, eb, tokof(k + 1));
;     __builtin_amdgcn_sched_barrier(0);
;     compute(ga, tokof(k));
.LBB0_1477:
	s_add_i32 s19, s1, -1
	v_min_i32_e32 v60, s19, v195
	s_waitcnt lgkmcnt(0)
	v_mad_u64_u32 v[60:61], s[8:9], v60, s18, v[194:195]
	v_ashrrev_i32_e32 v61, 31, v60
	v_lshlrev_b64 v[208:209], 9, v[60:61]
	v_lshl_add_u64 v[60:61], v[198:199], 0, v[208:209]
	s_add_i32 s16, s1, -2
	global_load_dwordx4 v[172:175], v[60:61], off offset:48
	global_load_dwordx4 v[176:179], v[60:61], off offset:32
	global_load_dwordx4 v[184:187], v[60:61], off offset:16
	global_load_dwordx4 v[188:191], v[60:61], off
	v_ashrrev_i32_e32 v235, 31, v204
	v_mov_b32_e32 v234, v204
	v_lshlrev_b64 v[234:235], 12, v[234:235]
	v_lshl_add_u64 v[234:235], v[202:203], 0, v[234:235]
	global_load_dwordx2 v[232:233], v[234:235], off
	v_min_i32_e32 v60, s16, v195
	v_mad_u64_u32 v[206:207], s[8:9], v60, s18, v[194:195]
	s_waitcnt vmcnt(5)
	v_ashrrev_i32_e32 v61, 31, v132
	v_mov_b32_e32 v60, v132
	v_ashrrev_i32_e32 v63, 31, v133
	v_mov_b32_e32 v62, v133
	v_lshlrev_b64 v[60:61], 7, v[60:61]
	v_lshlrev_b64 v[62:63], 7, v[62:63]
	v_lshl_add_u64 v[60:61], v[196:197], 0, v[60:61]
	v_lshl_add_u64 v[62:63], v[196:197], 0, v[62:63]
	global_load_dwordx4 v[168:171], v[60:61], off
	global_load_dwordx4 v[164:167], v[62:63], off
	v_ashrrev_i32_e32 v61, 31, v134
	v_mov_b32_e32 v60, v134
	v_ashrrev_i32_e32 v63, 31, v135
	v_mov_b32_e32 v62, v135
	v_lshlrev_b64 v[60:61], 7, v[60:61]
	v_lshlrev_b64 v[62:63], 7, v[62:63]
	v_lshl_add_u64 v[60:61], v[196:197], 0, v[60:61]
	v_lshl_add_u64 v[62:63], v[196:197], 0, v[62:63]
	global_load_dwordx4 v[160:163], v[60:61], off
	global_load_dwordx4 v[152:155], v[62:63], off
	v_ashrrev_i32_e32 v61, 31, v116
	v_mov_b32_e32 v60, v116
	v_ashrrev_i32_e32 v63, 31, v117
	v_mov_b32_e32 v62, v117
	v_lshlrev_b64 v[60:61], 7, v[60:61]
	v_lshlrev_b64 v[62:63], 7, v[62:63]
	v_lshl_add_u64 v[60:61], v[196:197], 0, v[60:61]
	v_lshl_add_u64 v[62:63], v[196:197], 0, v[62:63]
	global_load_dwordx4 v[148:151], v[60:61], off
	global_load_dwordx4 v[144:147], v[62:63], off
	v_ashrrev_i32_e32 v61, 31, v118
	v_mov_b32_e32 v60, v118
	v_ashrrev_i32_e32 v63, 31, v119
	v_mov_b32_e32 v62, v119
	v_lshlrev_b64 v[60:61], 7, v[60:61]
	v_lshlrev_b64 v[62:63], 7, v[62:63]
	v_lshl_add_u64 v[60:61], v[196:197], 0, v[60:61]
	v_lshl_add_u64 v[62:63], v[196:197], 0, v[62:63]
	global_load_dwordx4 v[140:143], v[60:61], off
	global_load_dwordx4 v[136:139], v[62:63], off
	v_ashrrev_i32_e32 v61, 31, v108
	v_mov_b32_e32 v60, v108
	v_ashrrev_i32_e32 v63, 31, v109
	v_mov_b32_e32 v62, v109
	v_lshlrev_b64 v[60:61], 7, v[60:61]
	v_lshlrev_b64 v[62:63], 7, v[62:63]
	v_lshl_add_u64 v[60:61], v[196:197], 0, v[60:61]
	v_lshl_add_u64 v[62:63], v[196:197], 0, v[62:63]
	global_load_dwordx4 v[128:131], v[60:61], off
	global_load_dwordx4 v[120:123], v[62:63], off
	v_ashrrev_i32_e32 v61, 31, v110
	v_mov_b32_e32 v60, v110
	v_ashrrev_i32_e32 v63, 31, v111
	v_mov_b32_e32 v62, v111
	v_lshlrev_b64 v[60:61], 7, v[60:61]
	v_lshlrev_b64 v[62:63], 7, v[62:63]
	v_lshl_add_u64 v[60:61], v[196:197], 0, v[60:61]
	v_lshl_add_u64 v[62:63], v[196:197], 0, v[62:63]
	global_load_dwordx4 v[112:115], v[60:61], off
	global_load_dwordx4 v[104:107], v[62:63], off
	v_ashrrev_i32_e32 v61, 31, v96
	v_mov_b32_e32 v60, v96
	v_ashrrev_i32_e32 v63, 31, v97
	v_mov_b32_e32 v62, v97
	v_lshlrev_b64 v[60:61], 7, v[60:61]
	v_lshlrev_b64 v[62:63], 7, v[62:63]
	v_lshl_add_u64 v[60:61], v[196:197], 0, v[60:61]
	v_lshl_add_u64 v[62:63], v[196:197], 0, v[62:63]
	global_load_dwordx4 v[100:103], v[60:61], off
	global_load_dwordx4 v[92:95], v[62:63], off
	v_ashrrev_i32_e32 v61, 31, v98
	v_mov_b32_e32 v60, v98
	v_ashrrev_i32_e32 v63, 31, v99
	v_mov_b32_e32 v62, v99
	v_ashrrev_i32_e32 v207, 31, v206
	v_lshlrev_b64 v[60:61], 7, v[60:61]
	v_lshlrev_b64 v[62:63], 7, v[62:63]
	v_lshlrev_b64 v[72:73], 9, v[206:207]
	v_lshl_add_u64 v[60:61], v[196:197], 0, v[60:61]
	v_lshl_add_u64 v[62:63], v[196:197], 0, v[62:63]
	v_lshl_add_u64 v[96:97], v[200:201], 0, v[72:73]
	global_load_dwordx4 v[68:71], v[60:61], off
	s_nop 0
	global_load_dwordx4 v[60:63], v[62:63], off
	s_nop 0
	global_load_dwordx4 v[72:75], v[96:97], off offset:48
	global_load_dwordx4 v[124:127], v[96:97], off offset:32
	global_load_dwordx4 v[156:159], v[96:97], off offset:16
	global_load_dwordx4 v[180:183], v[96:97], off
	v_cvt_pk_f32_fp8_e32 v[96:97], v88
	v_cvt_pk_f32_fp8_sdwa v[98:99], v88 src0_sel:WORD_1
	v_cvt_pk_f32_fp8_e32 v[108:109], v89
	v_cvt_pk_f32_fp8_sdwa v[88:89], v89 src0_sel:WORD_1
	v_cvt_pk_f32_fp8_e32 v[132:133], v84
	v_cvt_pk_f32_fp8_sdwa v[134:135], v84 src0_sel:WORD_1
	v_cvt_pk_f32_fp8_e32 v[216:217], v85
	v_cvt_pk_f32_fp8_sdwa v[84:85], v85 src0_sel:WORD_1
	v_pk_fma_f32 v[96:97], v[96:97], v[52:53], 0 op_sel_hi:[1,0,0]
	v_pk_fma_f32 v[98:99], v[98:99], v[52:53], 0 op_sel_hi:[1,0,0]
	v_pk_fma_f32 v[88:89], v[88:89], v[52:53], 0 op_sel_hi:[1,0,0]
	v_cvt_pk_f32_fp8_e32 v[110:111], v90
	v_cvt_pk_f32_fp8_sdwa v[116:117], v90 src0_sel:WORD_1
	v_cvt_pk_f32_fp8_e32 v[118:119], v91
	v_cvt_pk_f32_fp8_sdwa v[90:91], v91 src0_sel:WORD_1
	v_pk_fma_f32 v[96:97], v[132:133], v[52:53], v[96:97] op_sel:[0,1,0]
	v_pk_fma_f32 v[98:99], v[134:135], v[52:53], v[98:99] op_sel:[0,1,0]
	v_pk_fma_f32 v[84:85], v[84:85], v[52:53], v[88:89] op_sel:[0,1,0]
	v_cvt_pk_f32_fp8_e32 v[88:89], v86
	v_cvt_pk_f32_fp8_sdwa v[132:133], v86 src0_sel:WORD_1
	v_cvt_pk_f32_fp8_e32 v[134:135], v87
	v_cvt_pk_f32_fp8_sdwa v[86:87], v87 src0_sel:WORD_1
	v_pk_fma_f32 v[108:109], v[108:109], v[52:53], 0 op_sel_hi:[1,0,0]
	v_pk_fma_f32 v[110:111], v[110:111], v[52:53], 0 op_sel_hi:[1,0,0]
	v_pk_fma_f32 v[116:117], v[116:117], v[52:53], 0 op_sel_hi:[1,0,0]
	v_pk_fma_f32 v[118:119], v[118:119], v[52:53], 0 op_sel_hi:[1,0,0]
; DI void peer_v_phase(const Params& p) {
;     ...
; #pragma unroll
;     for (int i = 0; i < 16; ++i) {
;       const float wi = (i & 3) == 0 ? r.w[i >> 2].x : (i & 3) == 1 ? r.w[i >> 2].y : (i & 3) == 2 ? r.w[i >> 2].z : r.w[i >> 2].w;
;       const f32x2 w2 = {wi, wi};
; #pragma unroll
;       for (int j = 0; j < 4; ++j) {
;         const f32x2 lo = __builtin_amdgcn_cvt_pk_f32_fp8((int)r.v[i][j], false);
;         const f32x2 hi = __builtin_amdgcn_cvt_pk_f32_fp8((int)r.v[i][j], true);
;         o2[2 * j] = __builtin_elementwise_fma(lo, w2, o2[2 * j]);
;         o2[2 * j + 1] = __builtin_elementwise_fma(hi, w2, o2[2 * j + 1]);
;       }
;     }
	v_pk_fma_f32 v[90:91], v[90:91], v[52:53], 0 op_sel_hi:[1,0,0]
	v_pk_fma_f32 v[108:109], v[216:217], v[52:53], v[108:109] op_sel:[0,1,0]
	v_pk_fma_f32 v[88:89], v[88:89], v[52:53], v[110:111] op_sel:[0,1,0]
	v_pk_fma_f32 v[110:111], v[132:133], v[52:53], v[116:117] op_sel:[0,1,0]
	v_pk_fma_f32 v[116:117], v[134:135], v[52:53], v[118:119] op_sel:[0,1,0]
	v_pk_fma_f32 v[52:53], v[86:87], v[52:53], v[90:91] op_sel:[0,1,0]
	v_cvt_pk_f32_fp8_e32 v[86:87], v80
	v_cvt_pk_f32_fp8_sdwa v[90:91], v80 src0_sel:WORD_1
	v_cvt_pk_f32_fp8_e32 v[118:119], v81
	v_cvt_pk_f32_fp8_sdwa v[80:81], v81 src0_sel:WORD_1
	v_pk_fma_f32 v[86:87], v[86:87], v[54:55], v[96:97] op_sel_hi:[1,0,1]
	v_pk_fma_f32 v[90:91], v[90:91], v[54:55], v[98:99] op_sel_hi:[1,0,1]
	v_pk_fma_f32 v[96:97], v[118:119], v[54:55], v[108:109] op_sel_hi:[1,0,1]
	v_pk_fma_f32 v[80:81], v[80:81], v[54:55], v[84:85] op_sel_hi:[1,0,1]
	v_cvt_pk_f32_fp8_e32 v[84:85], v82
	v_cvt_pk_f32_fp8_sdwa v[98:99], v82 src0_sel:WORD_1
	v_cvt_pk_f32_fp8_e32 v[108:109], v83
	v_cvt_pk_f32_fp8_sdwa v[82:83], v83 src0_sel:WORD_1
	v_pk_fma_f32 v[84:85], v[84:85], v[54:55], v[88:89] op_sel_hi:[1,0,1]
	v_pk_fma_f32 v[88:89], v[98:99], v[54:55], v[110:111] op_sel_hi:[1,0,1]
	v_pk_fma_f32 v[98:99], v[108:109], v[54:55], v[116:117] op_sel_hi:[1,0,1]
	v_pk_fma_f32 v[52:53], v[82:83], v[54:55], v[52:53] op_sel_hi:[1,0,1]
	v_cvt_pk_f32_fp8_e32 v[82:83], v76
	v_cvt_pk_f32_fp8_sdwa v[108:109], v76 src0_sel:WORD_1
	v_cvt_pk_f32_fp8_e32 v[110:111], v77
	v_cvt_pk_f32_fp8_sdwa v[76:77], v77 src0_sel:WORD_1
	v_pk_fma_f32 v[82:83], v[82:83], v[54:55], v[86:87] op_sel:[0,1,0]
	v_pk_fma_f32 v[86:87], v[108:109], v[54:55], v[90:91] op_sel:[0,1,0]
	v_pk_fma_f32 v[90:91], v[110:111], v[54:55], v[96:97] op_sel:[0,1,0]
	v_pk_fma_f32 v[76:77], v[76:77], v[54:55], v[80:81] op_sel:[0,1,0]
	v_cvt_pk_f32_fp8_e32 v[80:81], v78
	v_cvt_pk_f32_fp8_sdwa v[96:97], v78 src0_sel:WORD_1
	v_cvt_pk_f32_fp8_e32 v[108:109], v79
	v_cvt_pk_f32_fp8_sdwa v[78:79], v79 src0_sel:WORD_1
	v_pk_fma_f32 v[80:81], v[80:81], v[54:55], v[84:85] op_sel:[0,1,0]
	v_pk_fma_f32 v[84:85], v[96:97], v[54:55], v[88:89] op_sel:[0,1,0]
	v_pk_fma_f32 v[88:89], v[108:109], v[54:55], v[98:99] op_sel:[0,1,0]
	v_pk_fma_f32 v[52:53], v[78:79], v[54:55], v[52:53] op_sel:[0,1,0]
	v_cvt_pk_f32_fp8_e32 v[54:55], v64
	v_cvt_pk_f32_fp8_sdwa v[78:79], v64 src0_sel:WORD_1
	v_cvt_pk_f32_fp8_e32 v[96:97], v65
	v_cvt_pk_f32_fp8_sdwa v[64:65], v65 src0_sel:WORD_1
	v_pk_fma_f32 v[54:55], v[54:55], v[28:29], v[82:83] op_sel_hi:[1,0,1]
	v_pk_fma_f32 v[78:79], v[78:79], v[28:29], v[86:87] op_sel_hi:[1,0,1]
	v_pk_fma_f32 v[82:83], v[96:97], v[28:29], v[90:91] op_sel_hi:[1,0,1]
	v_pk_fma_f32 v[64:65], v[64:65], v[28:29], v[76:77] op_sel_hi:[1,0,1]
	v_cvt_pk_f32_fp8_e32 v[76:77], v66
	v_cvt_pk_f32_fp8_sdwa v[86:87], v66 src0_sel:WORD_1
	v_cvt_pk_f32_fp8_e32 v[90:91], v67
	v_cvt_pk_f32_fp8_sdwa v[66:67], v67 src0_sel:WORD_1
	v_pk_fma_f32 v[76:77], v[76:77], v[28:29], v[80:81] op_sel_hi:[1,0,1]
	v_pk_fma_f32 v[80:81], v[86:87], v[28:29], v[84:85] op_sel_hi:[1,0,1]
	v_pk_fma_f32 v[84:85], v[90:91], v[28:29], v[88:89] op_sel_hi:[1,0,1]
	v_pk_fma_f32 v[52:53], v[66:67], v[28:29], v[52:53] op_sel_hi:[1,0,1]
	v_cvt_pk_f32_fp8_e32 v[66:67], v56
	v_cvt_pk_f32_fp8_sdwa v[86:87], v56 src0_sel:WORD_1
	v_cvt_pk_f32_fp8_e32 v[88:89], v57
	v_cvt_pk_f32_fp8_sdwa v[56:57], v57 src0_sel:WORD_1
	v_pk_fma_f32 v[54:55], v[66:67], v[28:29], v[54:55] op_sel:[0,1,0]
	v_pk_fma_f32 v[66:67], v[86:87], v[28:29], v[78:79] op_sel:[0,1,0]
	v_pk_fma_f32 v[78:79], v[88:89], v[28:29], v[82:83] op_sel:[0,1,0]
	v_pk_fma_f32 v[56:57], v[56:57], v[28:29], v[64:65] op_sel:[0,1,0]
	v_cvt_pk_f32_fp8_e32 v[64:65], v58
	v_cvt_pk_f32_fp8_sdwa v[82:83], v58 src0_sel:WORD_1
	v_cvt_pk_f32_fp8_e32 v[86:87], v59
	v_cvt_pk_f32_fp8_sdwa v[58:59], v59 src0_sel:WORD_1
	v_pk_fma_f32 v[64:65], v[64:65], v[28:29], v[76:77] op_sel:[0,1,0]
	v_pk_fma_f32 v[76:77], v[82:83], v[28:29], v[80:81] op_sel:[0,1,0]
	v_pk_fma_f32 v[80:81], v[86:87], v[28:29], v[84:85] op_sel:[0,1,0]
	v_pk_fma_f32 v[28:29], v[58:59], v[28:29], v[52:53] op_sel:[0,1,0]
	v_cvt_pk_f32_fp8_e32 v[52:53], v48
	v_cvt_pk_f32_fp8_sdwa v[58:59], v48 src0_sel:WORD_1
	v_cvt_pk_f32_fp8_e32 v[82:83], v49
	v_cvt_pk_f32_fp8_sdwa v[48:49], v49 src0_sel:WORD_1
	v_pk_fma_f32 v[52:53], v[52:53], v[30:31], v[54:55] op_sel_hi:[1,0,1]
	v_pk_fma_f32 v[54:55], v[58:59], v[30:31], v[66:67] op_sel_hi:[1,0,1]
	v_pk_fma_f32 v[58:59], v[82:83], v[30:31], v[78:79] op_sel_hi:[1,0,1]
	v_pk_fma_f32 v[48:49], v[48:49], v[30:31], v[56:57] op_sel_hi:[1,0,1]
	v_cvt_pk_f32_fp8_e32 v[56:57], v50
	v_cvt_pk_f32_fp8_sdwa v[66:67], v50 src0_sel:WORD_1
	v_cvt_pk_f32_fp8_e32 v[78:79], v51
	v_cvt_pk_f32_fp8_sdwa v[50:51], v51 src0_sel:WORD_1
	v_pk_fma_f32 v[56:57], v[56:57], v[30:31], v[64:65] op_sel_hi:[1,0,1]
	v_pk_fma_f32 v[64:65], v[66:67], v[30:31], v[76:77] op_sel_hi:[1,0,1]
	v_pk_fma_f32 v[66:67], v[78:79], v[30:31], v[80:81] op_sel_hi:[1,0,1]
	v_pk_fma_f32 v[28:29], v[50:51], v[30:31], v[28:29] op_sel_hi:[1,0,1]
	v_cvt_pk_f32_fp8_e32 v[50:51], v44
	v_cvt_pk_f32_fp8_sdwa v[76:77], v44 src0_sel:WORD_1
	v_cvt_pk_f32_fp8_e32 v[78:79], v45
	v_cvt_pk_f32_fp8_sdwa v[44:45], v45 src0_sel:WORD_1
	v_pk_fma_f32 v[50:51], v[50:51], v[30:31], v[52:53] op_sel:[0,1,0]
	v_pk_fma_f32 v[52:53], v[76:77], v[30:31], v[54:55] op_sel:[0,1,0]
	v_pk_fma_f32 v[54:55], v[78:79], v[30:31], v[58:59] op_sel:[0,1,0]
	v_pk_fma_f32 v[44:45], v[44:45], v[30:31], v[48:49] op_sel:[0,1,0]
	v_cvt_pk_f32_fp8_e32 v[48:49], v46
	v_cvt_pk_f32_fp8_sdwa v[58:59], v46 src0_sel:WORD_1
	v_cvt_pk_f32_fp8_e32 v[76:77], v47
	v_cvt_pk_f32_fp8_sdwa v[46:47], v47 src0_sel:WORD_1
; DI void peer_v_phase(const Params& p) {
;     ...
; #pragma unroll
;     for (int i = 0; i < 16; ++i) {
;       const float wi = (i & 3) == 0 ? r.w[i >> 2].x : (i & 3) == 1 ? r.w[i >> 2].y : (i & 3) == 2 ? r.w[i >> 2].z : r.w[i >> 2].w;
;       const f32x2 w2 = {wi, wi};
; #pragma unroll
;       for (int j = 0; j < 4; ++j) {
;         const f32x2 lo = __builtin_amdgcn_cvt_pk_f32_fp8((int)r.v[i][j], false);
;         const f32x2 hi = __builtin_amdgcn_cvt_pk_f32_fp8((int)r.v[i][j], true);
;         o2[2 * j] = __builtin_elementwise_fma(lo, w2, o2[2 * j]);
;         o2[2 * j + 1] = __builtin_elementwise_fma(hi, w2, o2[2 * j + 1]);
;       }
;     }
	v_pk_fma_f32 v[48:49], v[48:49], v[30:31], v[56:57] op_sel:[0,1,0]
	v_pk_fma_f32 v[56:57], v[58:59], v[30:31], v[64:65] op_sel:[0,1,0]
	v_pk_fma_f32 v[58:59], v[76:77], v[30:31], v[66:67] op_sel:[0,1,0]
	v_pk_fma_f32 v[28:29], v[46:47], v[30:31], v[28:29] op_sel:[0,1,0]
	v_cvt_pk_f32_fp8_e32 v[30:31], v40
	v_cvt_pk_f32_fp8_sdwa v[46:47], v40 src0_sel:WORD_1
	v_cvt_pk_f32_fp8_e32 v[64:65], v41
	v_cvt_pk_f32_fp8_sdwa v[40:41], v41 src0_sel:WORD_1
	v_pk_fma_f32 v[30:31], v[30:31], v[12:13], v[50:51] op_sel_hi:[1,0,1]
	v_pk_fma_f32 v[46:47], v[46:47], v[12:13], v[52:53] op_sel_hi:[1,0,1]
	v_pk_fma_f32 v[50:51], v[64:65], v[12:13], v[54:55] op_sel_hi:[1,0,1]
	v_pk_fma_f32 v[40:41], v[40:41], v[12:13], v[44:45] op_sel_hi:[1,0,1]
	v_cvt_pk_f32_fp8_e32 v[44:45], v42
	v_cvt_pk_f32_fp8_sdwa v[52:53], v42 src0_sel:WORD_1
	v_cvt_pk_f32_fp8_e32 v[54:55], v43
	v_cvt_pk_f32_fp8_sdwa v[42:43], v43 src0_sel:WORD_1
	v_pk_fma_f32 v[44:45], v[44:45], v[12:13], v[48:49] op_sel_hi:[1,0,1]
	v_pk_fma_f32 v[48:49], v[52:53], v[12:13], v[56:57] op_sel_hi:[1,0,1]
	v_pk_fma_f32 v[52:53], v[54:55], v[12:13], v[58:59] op_sel_hi:[1,0,1]
	v_pk_fma_f32 v[28:29], v[42:43], v[12:13], v[28:29] op_sel_hi:[1,0,1]
	v_cvt_pk_f32_fp8_e32 v[42:43], v36
	v_cvt_pk_f32_fp8_sdwa v[54:55], v36 src0_sel:WORD_1
	v_cvt_pk_f32_fp8_e32 v[56:57], v37
	v_cvt_pk_f32_fp8_sdwa v[36:37], v37 src0_sel:WORD_1
	v_pk_fma_f32 v[30:31], v[42:43], v[12:13], v[30:31] op_sel:[0,1,0]
	v_pk_fma_f32 v[42:43], v[54:55], v[12:13], v[46:47] op_sel:[0,1,0]
	v_pk_fma_f32 v[46:47], v[56:57], v[12:13], v[50:51] op_sel:[0,1,0]
	v_pk_fma_f32 v[36:37], v[36:37], v[12:13], v[40:41] op_sel:[0,1,0]
	v_cvt_pk_f32_fp8_e32 v[40:41], v38
	v_cvt_pk_f32_fp8_sdwa v[50:51], v38 src0_sel:WORD_1
	v_cvt_pk_f32_fp8_e32 v[54:55], v39
	v_cvt_pk_f32_fp8_sdwa v[38:39], v39 src0_sel:WORD_1
	v_pk_fma_f32 v[40:41], v[40:41], v[12:13], v[44:45] op_sel:[0,1,0]
	v_pk_fma_f32 v[44:45], v[50:51], v[12:13], v[48:49] op_sel:[0,1,0]
	v_pk_fma_f32 v[48:49], v[54:55], v[12:13], v[52:53] op_sel:[0,1,0]
	v_pk_fma_f32 v[12:13], v[38:39], v[12:13], v[28:29] op_sel:[0,1,0]
	v_cvt_pk_f32_fp8_e32 v[28:29], v32
	v_cvt_pk_f32_fp8_sdwa v[38:39], v32 src0_sel:WORD_1
	v_cvt_pk_f32_fp8_e32 v[50:51], v33
	v_cvt_pk_f32_fp8_sdwa v[32:33], v33 src0_sel:WORD_1
	v_pk_fma_f32 v[28:29], v[28:29], v[14:15], v[30:31] op_sel_hi:[1,0,1]
	v_pk_fma_f32 v[30:31], v[38:39], v[14:15], v[42:43] op_sel_hi:[1,0,1]
	v_pk_fma_f32 v[38:39], v[50:51], v[14:15], v[46:47] op_sel_hi:[1,0,1]
	v_pk_fma_f32 v[32:33], v[32:33], v[14:15], v[36:37] op_sel_hi:[1,0,1]
	v_cvt_pk_f32_fp8_e32 v[36:37], v34
	v_cvt_pk_f32_fp8_sdwa v[42:43], v34 src0_sel:WORD_1
	v_cvt_pk_f32_fp8_e32 v[46:47], v35
	v_cvt_pk_f32_fp8_sdwa v[34:35], v35 src0_sel:WORD_1
	v_pk_fma_f32 v[36:37], v[36:37], v[14:15], v[40:41] op_sel_hi:[1,0,1]
	v_pk_fma_f32 v[40:41], v[42:43], v[14:15], v[44:45] op_sel_hi:[1,0,1]
	v_pk_fma_f32 v[42:43], v[46:47], v[14:15], v[48:49] op_sel_hi:[1,0,1]
	v_pk_fma_f32 v[12:13], v[34:35], v[14:15], v[12:13] op_sel_hi:[1,0,1]
	v_cvt_pk_f32_fp8_e32 v[34:35], v24
	v_cvt_pk_f32_fp8_sdwa v[44:45], v24 src0_sel:WORD_1
	v_cvt_pk_f32_fp8_e32 v[46:47], v25
	v_cvt_pk_f32_fp8_sdwa v[24:25], v25 src0_sel:WORD_1
	v_pk_fma_f32 v[28:29], v[34:35], v[14:15], v[28:29] op_sel:[0,1,0]
	v_pk_fma_f32 v[30:31], v[44:45], v[14:15], v[30:31] op_sel:[0,1,0]
	v_pk_fma_f32 v[34:35], v[46:47], v[14:15], v[38:39] op_sel:[0,1,0]
	v_pk_fma_f32 v[24:25], v[24:25], v[14:15], v[32:33] op_sel:[0,1,0]
	v_cvt_pk_f32_fp8_e32 v[32:33], v26
	v_cvt_pk_f32_fp8_sdwa v[38:39], v26 src0_sel:WORD_1
	v_cvt_pk_f32_fp8_e32 v[44:45], v27
	v_cvt_pk_f32_fp8_sdwa v[26:27], v27 src0_sel:WORD_1
	v_pk_fma_f32 v[32:33], v[32:33], v[14:15], v[36:37] op_sel:[0,1,0]
	v_pk_fma_f32 v[36:37], v[38:39], v[14:15], v[40:41] op_sel:[0,1,0]
	v_pk_fma_f32 v[38:39], v[44:45], v[14:15], v[42:43] op_sel:[0,1,0]
	v_pk_fma_f32 v[12:13], v[26:27], v[14:15], v[12:13] op_sel:[0,1,0]
	v_cvt_pk_f32_fp8_e32 v[14:15], v20
	v_cvt_pk_f32_fp8_sdwa v[26:27], v20 src0_sel:WORD_1
	v_cvt_pk_f32_fp8_e32 v[40:41], v21
	v_cvt_pk_f32_fp8_sdwa v[20:21], v21 src0_sel:WORD_1
	v_pk_fma_f32 v[14:15], v[14:15], v[0:1], v[28:29] op_sel_hi:[1,0,1]
	v_pk_fma_f32 v[26:27], v[26:27], v[0:1], v[30:31] op_sel_hi:[1,0,1]
	v_pk_fma_f32 v[28:29], v[40:41], v[0:1], v[34:35] op_sel_hi:[1,0,1]
	v_pk_fma_f32 v[20:21], v[20:21], v[0:1], v[24:25] op_sel_hi:[1,0,1]
	v_cvt_pk_f32_fp8_e32 v[24:25], v22
	v_cvt_pk_f32_fp8_sdwa v[30:31], v22 src0_sel:WORD_1
	v_cvt_pk_f32_fp8_e32 v[34:35], v23
	v_cvt_pk_f32_fp8_sdwa v[22:23], v23 src0_sel:WORD_1
	v_pk_fma_f32 v[24:25], v[24:25], v[0:1], v[32:33] op_sel_hi:[1,0,1]
	v_pk_fma_f32 v[30:31], v[30:31], v[0:1], v[36:37] op_sel_hi:[1,0,1]
	v_pk_fma_f32 v[32:33], v[34:35], v[0:1], v[38:39] op_sel_hi:[1,0,1]
	v_pk_fma_f32 v[12:13], v[22:23], v[0:1], v[12:13] op_sel_hi:[1,0,1]
	v_cvt_pk_f32_fp8_e32 v[22:23], v16
	v_cvt_pk_f32_fp8_sdwa v[34:35], v16 src0_sel:WORD_1
	v_cvt_pk_f32_fp8_e32 v[36:37], v17
	v_cvt_pk_f32_fp8_sdwa v[16:17], v17 src0_sel:WORD_1
	v_pk_fma_f32 v[14:15], v[22:23], v[0:1], v[14:15] op_sel:[0,1,0]
	v_pk_fma_f32 v[22:23], v[34:35], v[0:1], v[26:27] op_sel:[0,1,0]
	v_pk_fma_f32 v[26:27], v[36:37], v[0:1], v[28:29] op_sel:[0,1,0]
	v_pk_fma_f32 v[16:17], v[16:17], v[0:1], v[20:21] op_sel:[0,1,0]
	v_cvt_pk_f32_fp8_e32 v[20:21], v18
	v_cvt_pk_f32_fp8_sdwa v[28:29], v18 src0_sel:WORD_1
	v_cvt_pk_f32_fp8_e32 v[34:35], v19
	v_ashrrev_i32_e32 v205, 31, v204
	v_pk_fma_f32 v[20:21], v[20:21], v[0:1], v[24:25] op_sel:[0,1,0]
	v_pk_fma_f32 v[24:25], v[28:29], v[0:1], v[30:31] op_sel:[0,1,0]
	v_pk_fma_f32 v[28:29], v[34:35], v[0:1], v[32:33] op_sel:[0,1,0]
; DI void peer_v_phase(const Params& p) {
;     ...
;     float o[16];
; #pragma unroll
;     for (int k = 0; k < 8; ++k) { o[2 * k] = o2[k][0]; o[2 * k + 1] = o2[k][1]; }
;     float r8[8], r4[4], r2[2];
; #pragma unroll
;     for (int k = 0; k < 8; ++k) {
;       const float keep = (lane & 32) ? o[k + 8] : o[k], send = (lane & 32) ? o[k] : o[k + 8];
;       r8[k] = keep + __shfl_xor(send, 32);
;     }
; #pragma unroll
;     for (int k = 0; k < 4; ++k) {
;       const float keep = (lane & 16) ? r8[k + 4] : r8[k], send = (lane & 16) ? r8[k] : r8[k + 4];
;       r4[k] = keep + __shfl_xor(send, 16);
;     }
; #pragma unroll
;     for (int k = 0; k < 2; ++k) {
;       const float keep = (lane & 8) ? r4[k + 2] : r4[k], send = (lane & 8) ? r4[k] : r4[k + 2];
;       r2[k] = keep + __shfl_xor(send, 8);
;     }
;     float* xr = p.out + (size_t)tok * 1024 + 128 * g + 16 * s + 2 * q;
;     float2 y = *(const float2*)xr;
;     y.x += r2[0]; y.y += r2[1];
;     *(float2*)xr = y;
;     const float ss = wave_sum(y.x * y.x + y.y * y.y);
;     if (lane == 0) SSP[tok] = ss;
	v_cvt_pk_f32_fp8_sdwa v[18:19], v19 src0_sel:WORD_1
	v_cvt_pk_f32_fp8_e32 v[30:31], v9
	v_pk_fma_f32 v[0:1], v[18:19], v[0:1], v[12:13] op_sel:[0,1,0]
	v_cvt_pk_f32_fp8_e32 v[12:13], v8
	v_cvt_pk_f32_fp8_sdwa v[18:19], v8 src0_sel:WORD_1
	v_cvt_pk_f32_fp8_sdwa v[8:9], v9 src0_sel:WORD_1
	v_pk_fma_f32 v[12:13], v[12:13], v[2:3], v[14:15] op_sel_hi:[1,0,1]
	v_pk_fma_f32 v[14:15], v[18:19], v[2:3], v[22:23] op_sel_hi:[1,0,1]
	v_pk_fma_f32 v[18:19], v[30:31], v[2:3], v[26:27] op_sel_hi:[1,0,1]
	v_pk_fma_f32 v[8:9], v[8:9], v[2:3], v[16:17] op_sel_hi:[1,0,1]
	v_cvt_pk_f32_fp8_e32 v[16:17], v10
	v_cvt_pk_f32_fp8_sdwa v[22:23], v10 src0_sel:WORD_1
	v_cvt_pk_f32_fp8_e32 v[26:27], v11
	v_cvt_pk_f32_fp8_sdwa v[10:11], v11 src0_sel:WORD_1
	v_pk_fma_f32 v[16:17], v[16:17], v[2:3], v[20:21] op_sel_hi:[1,0,1]
	v_pk_fma_f32 v[20:21], v[22:23], v[2:3], v[24:25] op_sel_hi:[1,0,1]
	v_pk_fma_f32 v[22:23], v[26:27], v[2:3], v[28:29] op_sel_hi:[1,0,1]
	v_pk_fma_f32 v[0:1], v[10:11], v[2:3], v[0:1] op_sel_hi:[1,0,1]
	v_cvt_pk_f32_fp8_e32 v[10:11], v4
	v_cvt_pk_f32_fp8_sdwa v[24:25], v4 src0_sel:WORD_1
	v_cvt_pk_f32_fp8_e32 v[26:27], v5
	v_cvt_pk_f32_fp8_sdwa v[4:5], v5 src0_sel:WORD_1
	v_pk_fma_f32 v[10:11], v[10:11], v[2:3], v[12:13] op_sel:[0,1,0]
	v_pk_fma_f32 v[12:13], v[24:25], v[2:3], v[14:15] op_sel:[0,1,0]
	v_pk_fma_f32 v[14:15], v[26:27], v[2:3], v[18:19] op_sel:[0,1,0]
	v_pk_fma_f32 v[4:5], v[4:5], v[2:3], v[8:9] op_sel:[0,1,0]
	v_cvt_pk_f32_fp8_e32 v[8:9], v6
	v_cvt_pk_f32_fp8_sdwa v[18:19], v6 src0_sel:WORD_1
	v_cvt_pk_f32_fp8_e32 v[24:25], v7
	v_cvt_pk_f32_fp8_sdwa v[6:7], v7 src0_sel:WORD_1
	v_pk_fma_f32 v[8:9], v[8:9], v[2:3], v[16:17] op_sel:[0,1,0]
	v_pk_fma_f32 v[16:17], v[18:19], v[2:3], v[20:21] op_sel:[0,1,0]
	v_pk_fma_f32 v[18:19], v[24:25], v[2:3], v[22:23] op_sel:[0,1,0]
	v_pk_fma_f32 v[0:1], v[6:7], v[2:3], v[0:1] op_sel:[0,1,0]
	v_cndmask_b32_e32 v2, v10, v8, vcc
	v_cndmask_b32_e32 v3, v11, v9, vcc
	ds_bpermute_b32 v2, v210, v2
	ds_bpermute_b32 v3, v210, v3
	v_cndmask_b32_e32 v6, v12, v16, vcc
	v_cndmask_b32_e32 v7, v13, v17, vcc
	ds_bpermute_b32 v6, v210, v6
	ds_bpermute_b32 v7, v210, v7
	v_cndmask_b32_e32 v20, v14, v18, vcc
	v_cndmask_b32_e32 v21, v15, v19, vcc
	ds_bpermute_b32 v20, v210, v20
	ds_bpermute_b32 v21, v210, v21
	v_cndmask_b32_e32 v22, v4, v0, vcc
	v_cndmask_b32_e32 v23, v5, v1, vcc
	ds_bpermute_b32 v22, v210, v22
	ds_bpermute_b32 v23, v210, v23
	v_cndmask_b32_e32 v9, v9, v11, vcc
	v_cndmask_b32_e32 v8, v8, v10, vcc
	s_waitcnt lgkmcnt(6)
	v_pk_add_f32 v[2:3], v[8:9], v[2:3]
	v_cndmask_b32_e32 v9, v17, v13, vcc
	v_cndmask_b32_e32 v8, v16, v12, vcc
	s_waitcnt lgkmcnt(4)
	v_pk_add_f32 v[6:7], v[8:9], v[6:7]
	v_cndmask_b32_e32 v9, v19, v15, vcc
	v_cndmask_b32_e32 v8, v18, v14, vcc
	s_waitcnt lgkmcnt(2)
	v_pk_add_f32 v[8:9], v[8:9], v[20:21]
	v_cndmask_b32_e32 v1, v1, v5, vcc
	v_cndmask_b32_e32 v0, v0, v4, vcc
	s_waitcnt lgkmcnt(0)
	v_pk_add_f32 v[0:1], v[0:1], v[22:23]
	v_cndmask_b32_e64 v11, v9, v3, s[2:3]
	v_cndmask_b32_e64 v3, v3, v9, s[2:3]
	ds_bpermute_b32 v5, v211, v3
	v_cndmask_b32_e64 v3, v6, v0, s[2:3]
	v_cndmask_b32_e64 v4, v2, v8, s[2:3]
	ds_bpermute_b32 v12, v211, v3
	v_cndmask_b32_e64 v3, v7, v1, s[2:3]
	ds_bpermute_b32 v4, v211, v4
	ds_bpermute_b32 v13, v211, v3
	v_cndmask_b32_e64 v10, v8, v2, s[2:3]
	v_cndmask_b32_e64 v1, v1, v7, s[2:3]
	v_cndmask_b32_e64 v0, v0, v6, s[2:3]
	s_waitcnt lgkmcnt(1)
	v_pk_add_f32 v[2:3], v[10:11], v[4:5]
	s_waitcnt lgkmcnt(0)
	v_pk_add_f32 v[0:1], v[0:1], v[12:13]
	s_nop 0
	v_cndmask_b32_e64 v4, v2, v0, s[4:5]
	v_cndmask_b32_e64 v5, v3, v1, s[4:5]
	ds_bpermute_b32 v4, v212, v4
	ds_bpermute_b32 v5, v212, v5
	v_cndmask_b32_e64 v1, v1, v3, s[4:5]
	v_cndmask_b32_e64 v0, v0, v2, s[4:5]
	s_waitcnt lgkmcnt(0)
	v_pk_add_f32 v[0:1], v[0:1], v[4:5]
	s_waitcnt vmcnt(0)
	v_pk_add_f32 v[2:3], v[0:1], v[232:233]
	global_store_dwordx2 v[234:235], v[2:3], off
	v_pk_mul_f32 v[0:1], v[2:3], v[2:3]
	s_nop 0
	v_add_f32_e32 v0, v0, v1
	s_nop 1
	v_add_f32_dpp v0, v0, v0 quad_perm:[1,0,3,2] row_mask:0xf bank_mask:0xf
	s_nop 1
	v_add_f32_dpp v0, v0, v0 quad_perm:[2,3,0,1] row_mask:0xf bank_mask:0xf
	s_nop 1
	v_add_f32_dpp v0, v0, v0 row_half_mirror row_mask:0xf bank_mask:0xf
	s_nop 1
	v_add_f32_dpp v0, v0, v0 row_mirror row_mask:0xf bank_mask:0xf
	s_nop 1
	v_add_f32_dpp v0, v0, v0 row_bcast:15 row_mask:0xa bank_mask:0xf
	s_nop 1
	v_add_f32_dpp v0, v0, v0 row_bcast:31 row_mask:0xc bank_mask:0xf
	s_and_saveexec_b64 s[8:9], s[6:7]
	s_cbranch_execz .LBB0_1479
	v_mov_b32_e32 v2, v0
	v_lshl_add_u64 v[0:1], v[204:205], 2, s[12:13]
	global_store_dword v[0:1], v2, off
; DI void peer_v_phase(const Params& p) {
;     ...
;   auto gather = [&](PeerVRows& r, const int* e, int tok) {
; #pragma unroll
;     for (int i = 0; i < 16; ++i) r.v[i] = *(const u32x4*)(Vb + (size_t)e[i] * 128);
;     const float4* wp = (const float4*)(W + (size_t)tok * 128 + 16 * q);
; #pragma unroll
;     for (int j = 0; j < 4; ++j) r.w[j] = wp[j];
;   };
;   auto compute = [&](const PeerVRows& r, int tok) {
;     f32x2 o2[8];
; #pragma unroll
;     for (int k = 0; k < 8; ++k) { o2[k][0] = 0.f; o2[k][1] = 0.f; }
; #pragma unroll
;     for (int i = 0; i < 16; ++i) {
;       const float wi = (i & 3) == 0 ? r.w[i >> 2].x : (i & 3) == 1 ? r.w[i >> 2].y : (i & 3) == 2 ? r.w[i >> 2].z : r.w[i >> 2].w;
;       const f32x2 w2 = {wi, wi};
; #pragma unroll
;       for (int j = 0; j < 4; ++j) {
;         const f32x2 lo = __builtin_amdgcn_cvt_pk_f32_fp8((int)r.v[i][j], false);
;         const f32x2 hi = __builtin_amdgcn_cvt_pk_f32_fp8((int)r.v[i][j], true);
;         o2[2 * j] = __builtin_elementwise_fma(lo, w2, o2[2 * j]);
;         o2[2 * j + 1] = __builtin_elementwise_fma(hi, w2, o2[2 * j + 1]);
;       }
;     }
;     ...
;     float* xr = p.out + (size_t)tok * 1024 + 128 * g + 16 * s + 2 * q;
;     float2 y = *(const float2*)xr;
;     y.x += r2[0]; y.y += r2[1];
;     *(float2*)xr = y;
;     const float ss = wave_sum(y.x * y.x + y.y * y.y);
;     if (lane == 0) SSP[tok] = ss;
;   };
;   int ea[16], eb[16];
;   PeerVRows ga, gb;
;   peer_load_e(ea, EID, tokof(0), q);
;   peer_load_e(eb, EID, tokof(1), q);
;   gather(ga, ea, tokof(0));
;   for (int k = 0; k < n; k += 2) {
;     peer_load_e(ea, EID, tokof(k + 2), q);
;     gather(gb, eb, tokof(k + 1));
;     __builtin_amdgcn_sched_barrier(0);
;     compute(ga, tokof(k));
;     __builtin_amdgcn_sched_barrier(0);
;     peer_load_e(eb, EID, tokof(k + 3), q);
;     gather(ga, ea, tokof(k + 2));
;     __builtin_amdgcn_sched_barrier(0);
;     if (k + 1 < n) compute(gb, tokof(k + 1));
.LBB0_1479:
	s_or_b64 exec, exec, s[8:9]
	v_min_i32_e32 v0, s1, v195
	s_waitcnt lgkmcnt(0)
	v_mad_u64_u32 v[0:1], s[8:9], v0, s18, v[194:195]
	v_ashrrev_i32_e32 v1, 31, v0
	v_lshlrev_b64 v[0:1], 9, v[0:1]
	v_lshl_add_u64 v[0:1], v[198:199], 0, v[0:1]
	global_load_dwordx4 v[96:99], v[0:1], off offset:48
	global_load_dwordx4 v[108:111], v[0:1], off offset:32
	global_load_dwordx4 v[116:119], v[0:1], off offset:16
	global_load_dwordx4 v[132:135], v[0:1], off
	v_lshlrev_b64 v[238:239], 12, v[206:207]
	v_lshl_add_u64 v[238:239], v[202:203], 0, v[238:239]
	global_load_dwordx2 v[236:237], v[238:239], off
	v_ashrrev_i32_e32 v1, 31, v188
	v_mov_b32_e32 v0, v188
	v_ashrrev_i32_e32 v3, 31, v189
	v_mov_b32_e32 v2, v189
	v_lshlrev_b64 v[0:1], 7, v[0:1]
	v_lshlrev_b64 v[2:3], 7, v[2:3]
	v_lshl_add_u64 v[0:1], v[196:197], 0, v[0:1]
	v_lshl_add_u64 v[2:3], v[196:197], 0, v[2:3]
	global_load_dwordx4 v[88:91], v[0:1], off
	global_load_dwordx4 v[84:87], v[2:3], off
	v_ashrrev_i32_e32 v1, 31, v190
	v_mov_b32_e32 v0, v190
	v_ashrrev_i32_e32 v3, 31, v191
	v_mov_b32_e32 v2, v191
	v_lshlrev_b64 v[0:1], 7, v[0:1]
	v_lshlrev_b64 v[2:3], 7, v[2:3]
	v_lshl_add_u64 v[0:1], v[196:197], 0, v[0:1]
	v_lshl_add_u64 v[2:3], v[196:197], 0, v[2:3]
	global_load_dwordx4 v[80:83], v[0:1], off
	global_load_dwordx4 v[76:79], v[2:3], off
	v_ashrrev_i32_e32 v1, 31, v184
	v_mov_b32_e32 v0, v184
	v_ashrrev_i32_e32 v3, 31, v185
	v_mov_b32_e32 v2, v185
	v_lshlrev_b64 v[0:1], 7, v[0:1]
	v_lshlrev_b64 v[2:3], 7, v[2:3]
	v_lshl_add_u64 v[0:1], v[196:197], 0, v[0:1]
	v_lshl_add_u64 v[2:3], v[196:197], 0, v[2:3]
	global_load_dwordx4 v[64:67], v[0:1], off
	global_load_dwordx4 v[56:59], v[2:3], off
	v_ashrrev_i32_e32 v1, 31, v186
	v_mov_b32_e32 v0, v186
	v_ashrrev_i32_e32 v3, 31, v187
	v_mov_b32_e32 v2, v187
	v_lshlrev_b64 v[0:1], 7, v[0:1]
	v_lshlrev_b64 v[2:3], 7, v[2:3]
	v_lshl_add_u64 v[0:1], v[196:197], 0, v[0:1]
	v_lshl_add_u64 v[2:3], v[196:197], 0, v[2:3]
	global_load_dwordx4 v[48:51], v[0:1], off
	global_load_dwordx4 v[44:47], v[2:3], off
	v_ashrrev_i32_e32 v1, 31, v176
	v_mov_b32_e32 v0, v176
	v_ashrrev_i32_e32 v3, 31, v177
	v_mov_b32_e32 v2, v177
	v_lshlrev_b64 v[0:1], 7, v[0:1]
	v_lshlrev_b64 v[2:3], 7, v[2:3]
	v_lshl_add_u64 v[0:1], v[196:197], 0, v[0:1]
	v_lshl_add_u64 v[2:3], v[196:197], 0, v[2:3]
	global_load_dwordx4 v[40:43], v[0:1], off
	global_load_dwordx4 v[36:39], v[2:3], off
	v_ashrrev_i32_e32 v1, 31, v178
	v_mov_b32_e32 v0, v178
	v_ashrrev_i32_e32 v3, 31, v179
	v_mov_b32_e32 v2, v179
	v_lshlrev_b64 v[0:1], 7, v[0:1]
	v_lshlrev_b64 v[2:3], 7, v[2:3]
	v_lshl_add_u64 v[0:1], v[196:197], 0, v[0:1]
	v_lshl_add_u64 v[2:3], v[196:197], 0, v[2:3]
	global_load_dwordx4 v[32:35], v[0:1], off
	global_load_dwordx4 v[24:27], v[2:3], off
	v_ashrrev_i32_e32 v1, 31, v172
	v_mov_b32_e32 v0, v172
	v_ashrrev_i32_e32 v3, 31, v173
	v_mov_b32_e32 v2, v173
	v_lshlrev_b64 v[0:1], 7, v[0:1]
	v_lshlrev_b64 v[2:3], 7, v[2:3]
	v_lshl_add_u64 v[0:1], v[196:197], 0, v[0:1]
	v_lshl_add_u64 v[2:3], v[196:197], 0, v[2:3]
	global_load_dwordx4 v[20:23], v[0:1], off
	global_load_dwordx4 v[16:19], v[2:3], off
	v_ashrrev_i32_e32 v1, 31, v174
	v_mov_b32_e32 v0, v174
	v_ashrrev_i32_e32 v3, 31, v175
	v_mov_b32_e32 v2, v175
	v_lshlrev_b64 v[0:1], 7, v[0:1]
	v_lshlrev_b64 v[2:3], 7, v[2:3]
	v_lshl_add_u64 v[0:1], v[196:197], 0, v[0:1]
	v_lshl_add_u64 v[2:3], v[196:197], 0, v[2:3]
	v_lshl_add_u64 v[52:53], v[200:201], 0, v[208:209]
	global_load_dwordx4 v[8:11], v[0:1], off
	global_load_dwordx4 v[4:7], v[2:3], off
	s_nop 0
	global_load_dwordx4 v[0:3], v[52:53], off offset:48
	global_load_dwordx4 v[12:15], v[52:53], off offset:32
	global_load_dwordx4 v[28:31], v[52:53], off offset:16
	s_nop 0
	global_load_dwordx4 v[52:55], v[52:53], off
	v_cmp_lt_i32_e64 s[8:9], s16, v193
	s_and_saveexec_b64 s[16:17], s[8:9]
	s_cbranch_execz .LBB0_1476
	v_cvt_pk_f32_fp8_e32 v[172:173], v168
	v_cvt_pk_f32_fp8_sdwa v[174:175], v168 src0_sel:WORD_1
	v_cvt_pk_f32_fp8_e32 v[176:177], v169
	v_cvt_pk_f32_fp8_sdwa v[168:169], v169 src0_sel:WORD_1
	v_cvt_pk_f32_fp8_e32 v[188:189], v164
	v_cvt_pk_f32_fp8_sdwa v[190:191], v164 src0_sel:WORD_1
	v_cvt_pk_f32_fp8_e32 v[208:209], v165
	v_cvt_pk_f32_fp8_sdwa v[164:165], v165 src0_sel:WORD_1
	v_pk_fma_f32 v[172:173], v[172:173], v[180:181], 0 op_sel_hi:[1,0,0]
	v_pk_fma_f32 v[174:175], v[174:175], v[180:181], 0 op_sel_hi:[1,0,0]
	v_pk_fma_f32 v[168:169], v[168:169], v[180:181], 0 op_sel_hi:[1,0,0]
	v_cvt_pk_f32_fp8_e32 v[178:179], v170
	v_cvt_pk_f32_fp8_sdwa v[184:185], v170 src0_sel:WORD_1
	v_cvt_pk_f32_fp8_e32 v[186:187], v171
	v_cvt_pk_f32_fp8_sdwa v[170:171], v171 src0_sel:WORD_1
	v_pk_fma_f32 v[172:173], v[188:189], v[180:181], v[172:173] op_sel:[0,1,0]
	v_pk_fma_f32 v[174:175], v[190:191], v[180:181], v[174:175] op_sel:[0,1,0]
	v_pk_fma_f32 v[164:165], v[164:165], v[180:181], v[168:169] op_sel:[0,1,0]
	v_cvt_pk_f32_fp8_e32 v[168:169], v166
	v_cvt_pk_f32_fp8_sdwa v[188:189], v166 src0_sel:WORD_1
	v_cvt_pk_f32_fp8_e32 v[190:191], v167
	v_cvt_pk_f32_fp8_sdwa v[166:167], v167 src0_sel:WORD_1
	v_pk_fma_f32 v[176:177], v[176:177], v[180:181], 0 op_sel_hi:[1,0,0]
	v_pk_fma_f32 v[178:179], v[178:179], v[180:181], 0 op_sel_hi:[1,0,0]
	v_pk_fma_f32 v[184:185], v[184:185], v[180:181], 0 op_sel_hi:[1,0,0]
	v_pk_fma_f32 v[186:187], v[186:187], v[180:181], 0 op_sel_hi:[1,0,0]
	v_pk_fma_f32 v[170:171], v[170:171], v[180:181], 0 op_sel_hi:[1,0,0]
	v_pk_fma_f32 v[176:177], v[208:209], v[180:181], v[176:177] op_sel:[0,1,0]
	v_pk_fma_f32 v[168:169], v[168:169], v[180:181], v[178:179] op_sel:[0,1,0]
	v_pk_fma_f32 v[178:179], v[188:189], v[180:181], v[184:185] op_sel:[0,1,0]
; DI void peer_v_phase(const Params& p) {
;     ...
;     for (int i = 0; i < 16; ++i) {
;       const float wi = (i & 3) == 0 ? r.w[i >> 2].x : (i & 3) == 1 ? r.w[i >> 2].y : (i & 3) == 2 ? r.w[i >> 2].z : r.w[i >> 2].w;
;       const f32x2 w2 = {wi, wi};
; #pragma unroll
;       for (int j = 0; j < 4; ++j) {
;         const f32x2 lo = __builtin_amdgcn_cvt_pk_f32_fp8((int)r.v[i][j], false);
;         const f32x2 hi = __builtin_amdgcn_cvt_pk_f32_fp8((int)r.v[i][j], true);
;         o2[2 * j] = __builtin_elementwise_fma(lo, w2, o2[2 * j]);
;         o2[2 * j + 1] = __builtin_elementwise_fma(hi, w2, o2[2 * j + 1]);
;       }
;     }
	v_pk_fma_f32 v[184:185], v[190:191], v[180:181], v[186:187] op_sel:[0,1,0]
	v_pk_fma_f32 v[166:167], v[166:167], v[180:181], v[170:171] op_sel:[0,1,0]
	v_cvt_pk_f32_fp8_e32 v[170:171], v160
	v_cvt_pk_f32_fp8_sdwa v[180:181], v160 src0_sel:WORD_1
	v_cvt_pk_f32_fp8_e32 v[186:187], v161
	v_cvt_pk_f32_fp8_sdwa v[160:161], v161 src0_sel:WORD_1
	v_pk_fma_f32 v[170:171], v[170:171], v[182:183], v[172:173] op_sel_hi:[1,0,1]
	v_pk_fma_f32 v[172:173], v[180:181], v[182:183], v[174:175] op_sel_hi:[1,0,1]
	v_pk_fma_f32 v[174:175], v[186:187], v[182:183], v[176:177] op_sel_hi:[1,0,1]
	v_pk_fma_f32 v[160:161], v[160:161], v[182:183], v[164:165] op_sel_hi:[1,0,1]
	v_cvt_pk_f32_fp8_e32 v[164:165], v162
	v_cvt_pk_f32_fp8_sdwa v[176:177], v162 src0_sel:WORD_1
	v_cvt_pk_f32_fp8_e32 v[180:181], v163
	v_cvt_pk_f32_fp8_sdwa v[162:163], v163 src0_sel:WORD_1
	v_pk_fma_f32 v[164:165], v[164:165], v[182:183], v[168:169] op_sel_hi:[1,0,1]
	v_pk_fma_f32 v[168:169], v[176:177], v[182:183], v[178:179] op_sel_hi:[1,0,1]
	v_pk_fma_f32 v[176:177], v[180:181], v[182:183], v[184:185] op_sel_hi:[1,0,1]
	v_pk_fma_f32 v[162:163], v[162:163], v[182:183], v[166:167] op_sel_hi:[1,0,1]
	v_mov_b32_e32 v166, v183
	v_cvt_pk_f32_fp8_e32 v[178:179], v152
	v_cvt_pk_f32_fp8_sdwa v[180:181], v152 src0_sel:WORD_1
	v_cvt_pk_f32_fp8_e32 v[182:183], v153
	v_cvt_pk_f32_fp8_sdwa v[152:153], v153 src0_sel:WORD_1
	v_pk_fma_f32 v[170:171], v[178:179], v[166:167], v[170:171] op_sel_hi:[1,0,1]
	v_pk_fma_f32 v[172:173], v[180:181], v[166:167], v[172:173] op_sel_hi:[1,0,1]
	v_cvt_pk_f32_fp8_sdwa v[178:179], v154 src0_sel:WORD_1
	v_pk_fma_f32 v[152:153], v[152:153], v[166:167], v[160:161] op_sel_hi:[1,0,1]
	v_cvt_pk_f32_fp8_e32 v[160:161], v154
	v_cvt_pk_f32_fp8_e32 v[180:181], v155
	v_cvt_pk_f32_fp8_sdwa v[154:155], v155 src0_sel:WORD_1
	v_pk_fma_f32 v[174:175], v[182:183], v[166:167], v[174:175] op_sel_hi:[1,0,1]
	v_pk_fma_f32 v[160:161], v[160:161], v[166:167], v[164:165] op_sel_hi:[1,0,1]
	v_pk_fma_f32 v[164:165], v[178:179], v[166:167], v[168:169] op_sel_hi:[1,0,1]
	v_pk_fma_f32 v[168:169], v[180:181], v[166:167], v[176:177] op_sel_hi:[1,0,1]
	v_pk_fma_f32 v[154:155], v[154:155], v[166:167], v[162:163] op_sel_hi:[1,0,1]
	v_cvt_pk_f32_fp8_e32 v[162:163], v148
	v_cvt_pk_f32_fp8_sdwa v[166:167], v148 src0_sel:WORD_1
	v_cvt_pk_f32_fp8_e32 v[176:177], v149
	v_cvt_pk_f32_fp8_sdwa v[148:149], v149 src0_sel:WORD_1
	v_pk_fma_f32 v[162:163], v[162:163], v[156:157], v[170:171] op_sel_hi:[1,0,1]
	v_pk_fma_f32 v[166:167], v[166:167], v[156:157], v[172:173] op_sel_hi:[1,0,1]
	v_pk_fma_f32 v[170:171], v[176:177], v[156:157], v[174:175] op_sel_hi:[1,0,1]
	v_pk_fma_f32 v[148:149], v[148:149], v[156:157], v[152:153] op_sel_hi:[1,0,1]
	v_cvt_pk_f32_fp8_e32 v[152:153], v150
	v_cvt_pk_f32_fp8_sdwa v[172:173], v150 src0_sel:WORD_1
	v_cvt_pk_f32_fp8_e32 v[174:175], v151
	v_cvt_pk_f32_fp8_sdwa v[150:151], v151 src0_sel:WORD_1
	v_pk_fma_f32 v[152:153], v[152:153], v[156:157], v[160:161] op_sel_hi:[1,0,1]
	v_pk_fma_f32 v[160:161], v[172:173], v[156:157], v[164:165] op_sel_hi:[1,0,1]
	v_pk_fma_f32 v[164:165], v[174:175], v[156:157], v[168:169] op_sel_hi:[1,0,1]
	v_pk_fma_f32 v[150:151], v[150:151], v[156:157], v[154:155] op_sel_hi:[1,0,1]
	v_mov_b32_e32 v154, v157
	v_cvt_pk_f32_fp8_e32 v[156:157], v144
	v_cvt_pk_f32_fp8_sdwa v[168:169], v144 src0_sel:WORD_1
	v_cvt_pk_f32_fp8_e32 v[172:173], v145
	v_cvt_pk_f32_fp8_sdwa v[144:145], v145 src0_sel:WORD_1
	v_pk_fma_f32 v[156:157], v[156:157], v[154:155], v[162:163] op_sel_hi:[1,0,1]
	v_pk_fma_f32 v[162:163], v[168:169], v[154:155], v[166:167] op_sel_hi:[1,0,1]
	v_pk_fma_f32 v[166:167], v[172:173], v[154:155], v[170:171] op_sel_hi:[1,0,1]
	v_pk_fma_f32 v[144:145], v[144:145], v[154:155], v[148:149] op_sel_hi:[1,0,1]
	v_cvt_pk_f32_fp8_e32 v[148:149], v146
	v_cvt_pk_f32_fp8_sdwa v[168:169], v146 src0_sel:WORD_1
	v_cvt_pk_f32_fp8_e32 v[170:171], v147
	v_cvt_pk_f32_fp8_sdwa v[146:147], v147 src0_sel:WORD_1
	v_pk_fma_f32 v[148:149], v[148:149], v[154:155], v[152:153] op_sel_hi:[1,0,1]
	v_pk_fma_f32 v[152:153], v[168:169], v[154:155], v[160:161] op_sel_hi:[1,0,1]
	v_pk_fma_f32 v[160:161], v[170:171], v[154:155], v[164:165] op_sel_hi:[1,0,1]
	v_pk_fma_f32 v[146:147], v[146:147], v[154:155], v[150:151] op_sel_hi:[1,0,1]
	v_cvt_pk_f32_fp8_e32 v[150:151], v140
	v_cvt_pk_f32_fp8_sdwa v[154:155], v140 src0_sel:WORD_1
	v_cvt_pk_f32_fp8_e32 v[164:165], v141
	v_cvt_pk_f32_fp8_sdwa v[140:141], v141 src0_sel:WORD_1
	v_pk_fma_f32 v[150:151], v[150:151], v[158:159], v[156:157] op_sel_hi:[1,0,1]
	v_pk_fma_f32 v[154:155], v[154:155], v[158:159], v[162:163] op_sel_hi:[1,0,1]
	v_pk_fma_f32 v[156:157], v[164:165], v[158:159], v[166:167] op_sel_hi:[1,0,1]
	v_pk_fma_f32 v[140:141], v[140:141], v[158:159], v[144:145] op_sel_hi:[1,0,1]
	v_cvt_pk_f32_fp8_e32 v[144:145], v142
	v_cvt_pk_f32_fp8_sdwa v[162:163], v142 src0_sel:WORD_1
	v_cvt_pk_f32_fp8_e32 v[164:165], v143
	v_cvt_pk_f32_fp8_sdwa v[142:143], v143 src0_sel:WORD_1
	v_pk_fma_f32 v[144:145], v[144:145], v[158:159], v[148:149] op_sel_hi:[1,0,1]
	v_pk_fma_f32 v[148:149], v[162:163], v[158:159], v[152:153] op_sel_hi:[1,0,1]
	v_pk_fma_f32 v[152:153], v[164:165], v[158:159], v[160:161] op_sel_hi:[1,0,1]
	v_pk_fma_f32 v[142:143], v[142:143], v[158:159], v[146:147] op_sel_hi:[1,0,1]
	v_mov_b32_e32 v146, v159
	v_cvt_pk_f32_fp8_e32 v[158:159], v136
	v_cvt_pk_f32_fp8_sdwa v[160:161], v136 src0_sel:WORD_1
	v_cvt_pk_f32_fp8_e32 v[162:163], v137
	v_cvt_pk_f32_fp8_sdwa v[136:137], v137 src0_sel:WORD_1
	v_pk_fma_f32 v[150:151], v[158:159], v[146:147], v[150:151] op_sel_hi:[1,0,1]
	v_pk_fma_f32 v[154:155], v[160:161], v[146:147], v[154:155] op_sel_hi:[1,0,1]
; DI void peer_v_phase(const Params& p) {
;     ...
;     for (int i = 0; i < 16; ++i) {
;       const float wi = (i & 3) == 0 ? r.w[i >> 2].x : (i & 3) == 1 ? r.w[i >> 2].y : (i & 3) == 2 ? r.w[i >> 2].z : r.w[i >> 2].w;
;       const f32x2 w2 = {wi, wi};
; #pragma unroll
;       for (int j = 0; j < 4; ++j) {
;         const f32x2 lo = __builtin_amdgcn_cvt_pk_f32_fp8((int)r.v[i][j], false);
;         const f32x2 hi = __builtin_amdgcn_cvt_pk_f32_fp8((int)r.v[i][j], true);
;         o2[2 * j] = __builtin_elementwise_fma(lo, w2, o2[2 * j]);
;         o2[2 * j + 1] = __builtin_elementwise_fma(hi, w2, o2[2 * j + 1]);
;       }
;     }
	v_cvt_pk_f32_fp8_sdwa v[158:159], v138 src0_sel:WORD_1
	v_pk_fma_f32 v[136:137], v[136:137], v[146:147], v[140:141] op_sel_hi:[1,0,1]
	v_cvt_pk_f32_fp8_e32 v[140:141], v138
	v_cvt_pk_f32_fp8_e32 v[160:161], v139
	v_cvt_pk_f32_fp8_sdwa v[138:139], v139 src0_sel:WORD_1
	v_pk_fma_f32 v[156:157], v[162:163], v[146:147], v[156:157] op_sel_hi:[1,0,1]
	v_pk_fma_f32 v[140:141], v[140:141], v[146:147], v[144:145] op_sel_hi:[1,0,1]
	v_pk_fma_f32 v[144:145], v[158:159], v[146:147], v[148:149] op_sel_hi:[1,0,1]
	v_pk_fma_f32 v[148:149], v[160:161], v[146:147], v[152:153] op_sel_hi:[1,0,1]
	v_pk_fma_f32 v[138:139], v[138:139], v[146:147], v[142:143] op_sel_hi:[1,0,1]
	v_cvt_pk_f32_fp8_e32 v[142:143], v128
	v_cvt_pk_f32_fp8_sdwa v[146:147], v128 src0_sel:WORD_1
	v_cvt_pk_f32_fp8_e32 v[152:153], v129
	v_cvt_pk_f32_fp8_sdwa v[128:129], v129 src0_sel:WORD_1
	v_pk_fma_f32 v[142:143], v[142:143], v[124:125], v[150:151] op_sel_hi:[1,0,1]
	v_pk_fma_f32 v[146:147], v[146:147], v[124:125], v[154:155] op_sel_hi:[1,0,1]
	v_pk_fma_f32 v[150:151], v[152:153], v[124:125], v[156:157] op_sel_hi:[1,0,1]
	v_pk_fma_f32 v[128:129], v[128:129], v[124:125], v[136:137] op_sel_hi:[1,0,1]
	v_cvt_pk_f32_fp8_e32 v[136:137], v130
	v_cvt_pk_f32_fp8_sdwa v[152:153], v130 src0_sel:WORD_1
	v_cvt_pk_f32_fp8_e32 v[154:155], v131
	v_cvt_pk_f32_fp8_sdwa v[130:131], v131 src0_sel:WORD_1
	v_pk_fma_f32 v[136:137], v[136:137], v[124:125], v[140:141] op_sel_hi:[1,0,1]
	v_pk_fma_f32 v[140:141], v[152:153], v[124:125], v[144:145] op_sel_hi:[1,0,1]
	v_pk_fma_f32 v[144:145], v[154:155], v[124:125], v[148:149] op_sel_hi:[1,0,1]
	v_pk_fma_f32 v[130:131], v[130:131], v[124:125], v[138:139] op_sel_hi:[1,0,1]
	v_cvt_pk_f32_fp8_e32 v[138:139], v120
	v_cvt_pk_f32_fp8_sdwa v[148:149], v120 src0_sel:WORD_1
	v_cvt_pk_f32_fp8_e32 v[152:153], v121
	v_cvt_pk_f32_fp8_sdwa v[120:121], v121 src0_sel:WORD_1
	v_mov_b32_e32 v124, v125
	v_pk_fma_f32 v[138:139], v[138:139], v[124:125], v[142:143] op_sel_hi:[1,0,1]
	v_pk_fma_f32 v[142:143], v[148:149], v[124:125], v[146:147] op_sel_hi:[1,0,1]
	v_pk_fma_f32 v[146:147], v[152:153], v[124:125], v[150:151] op_sel_hi:[1,0,1]
	v_pk_fma_f32 v[120:121], v[120:121], v[124:125], v[128:129] op_sel_hi:[1,0,1]
	v_cvt_pk_f32_fp8_e32 v[128:129], v122
	v_cvt_pk_f32_fp8_sdwa v[148:149], v122 src0_sel:WORD_1
	v_cvt_pk_f32_fp8_e32 v[150:151], v123
	v_cvt_pk_f32_fp8_sdwa v[122:123], v123 src0_sel:WORD_1
	v_pk_fma_f32 v[128:129], v[128:129], v[124:125], v[136:137] op_sel_hi:[1,0,1]
	v_pk_fma_f32 v[136:137], v[148:149], v[124:125], v[140:141] op_sel_hi:[1,0,1]
	v_pk_fma_f32 v[140:141], v[150:151], v[124:125], v[144:145] op_sel_hi:[1,0,1]
	v_pk_fma_f32 v[122:123], v[122:123], v[124:125], v[130:131] op_sel_hi:[1,0,1]
	v_cvt_pk_f32_fp8_e32 v[124:125], v112
	v_cvt_pk_f32_fp8_sdwa v[130:131], v112 src0_sel:WORD_1
	v_cvt_pk_f32_fp8_e32 v[144:145], v113
	v_cvt_pk_f32_fp8_sdwa v[112:113], v113 src0_sel:WORD_1
	v_pk_fma_f32 v[124:125], v[124:125], v[126:127], v[138:139] op_sel_hi:[1,0,1]
	v_pk_fma_f32 v[130:131], v[130:131], v[126:127], v[142:143] op_sel_hi:[1,0,1]
	v_pk_fma_f32 v[138:139], v[144:145], v[126:127], v[146:147] op_sel_hi:[1,0,1]
	v_pk_fma_f32 v[112:113], v[112:113], v[126:127], v[120:121] op_sel_hi:[1,0,1]
	v_cvt_pk_f32_fp8_e32 v[120:121], v114
	v_cvt_pk_f32_fp8_sdwa v[142:143], v114 src0_sel:WORD_1
	v_cvt_pk_f32_fp8_e32 v[144:145], v115
	v_cvt_pk_f32_fp8_sdwa v[114:115], v115 src0_sel:WORD_1
	v_pk_fma_f32 v[120:121], v[120:121], v[126:127], v[128:129] op_sel_hi:[1,0,1]
	v_pk_fma_f32 v[128:129], v[142:143], v[126:127], v[136:137] op_sel_hi:[1,0,1]
	v_pk_fma_f32 v[136:137], v[144:145], v[126:127], v[140:141] op_sel_hi:[1,0,1]
	v_pk_fma_f32 v[114:115], v[114:115], v[126:127], v[122:123] op_sel_hi:[1,0,1]
	v_cvt_pk_f32_fp8_e32 v[122:123], v104
	v_cvt_pk_f32_fp8_sdwa v[140:141], v104 src0_sel:WORD_1
	v_cvt_pk_f32_fp8_e32 v[142:143], v105
	v_cvt_pk_f32_fp8_sdwa v[104:105], v105 src0_sel:WORD_1
	v_mov_b32_e32 v126, v127
	v_pk_fma_f32 v[122:123], v[122:123], v[126:127], v[124:125] op_sel_hi:[1,0,1]
	v_pk_fma_f32 v[124:125], v[140:141], v[126:127], v[130:131] op_sel_hi:[1,0,1]
	v_pk_fma_f32 v[130:131], v[142:143], v[126:127], v[138:139] op_sel_hi:[1,0,1]
	v_cvt_pk_f32_fp8_e32 v[138:139], v106
	v_pk_fma_f32 v[104:105], v[104:105], v[126:127], v[112:113] op_sel_hi:[1,0,1]
	v_cvt_pk_f32_fp8_sdwa v[112:113], v106 src0_sel:WORD_1
	v_cvt_pk_f32_fp8_e32 v[140:141], v107
	v_cvt_pk_f32_fp8_sdwa v[106:107], v107 src0_sel:WORD_1
	v_pk_fma_f32 v[120:121], v[138:139], v[126:127], v[120:121] op_sel_hi:[1,0,1]
	v_pk_fma_f32 v[112:113], v[112:113], v[126:127], v[128:129] op_sel_hi:[1,0,1]
	v_pk_fma_f32 v[128:129], v[140:141], v[126:127], v[136:137] op_sel_hi:[1,0,1]
	v_pk_fma_f32 v[106:107], v[106:107], v[126:127], v[114:115] op_sel_hi:[1,0,1]
	v_cvt_pk_f32_fp8_sdwa v[114:115], v100 src0_sel:WORD_1
	v_cvt_pk_f32_fp8_e32 v[126:127], v101
	v_cvt_pk_f32_fp8_e32 v[136:137], v100
	v_cvt_pk_f32_fp8_sdwa v[100:101], v101 src0_sel:WORD_1
	v_pk_fma_f32 v[114:115], v[114:115], v[72:73], v[124:125] op_sel_hi:[1,0,1]
	v_pk_fma_f32 v[124:125], v[126:127], v[72:73], v[130:131] op_sel_hi:[1,0,1]
	v_cvt_pk_f32_fp8_e32 v[126:127], v102
	v_pk_fma_f32 v[100:101], v[100:101], v[72:73], v[104:105] op_sel_hi:[1,0,1]
	v_cvt_pk_f32_fp8_sdwa v[104:105], v102 src0_sel:WORD_1
	v_cvt_pk_f32_fp8_e32 v[130:131], v103
	v_cvt_pk_f32_fp8_sdwa v[102:103], v103 src0_sel:WORD_1
	v_pk_fma_f32 v[120:121], v[126:127], v[72:73], v[120:121] op_sel_hi:[1,0,1]
	v_cvt_pk_f32_fp8_e32 v[126:127], v92
	v_pk_fma_f32 v[122:123], v[136:137], v[72:73], v[122:123] op_sel_hi:[1,0,1]
	v_pk_fma_f32 v[102:103], v[102:103], v[72:73], v[106:107] op_sel_hi:[1,0,1]
; DI void peer_v_phase(const Params& p) {
;     ...
;       for (int j = 0; j < 4; ++j) {
;         const f32x2 lo = __builtin_amdgcn_cvt_pk_f32_fp8((int)r.v[i][j], false);
;         const f32x2 hi = __builtin_amdgcn_cvt_pk_f32_fp8((int)r.v[i][j], true);
;         o2[2 * j] = __builtin_elementwise_fma(lo, w2, o2[2 * j]);
;         o2[2 * j + 1] = __builtin_elementwise_fma(hi, w2, o2[2 * j + 1]);
;       }
;     }
;     float o[16];
; #pragma unroll
;     for (int k = 0; k < 8; ++k) { o[2 * k] = o2[k][0]; o[2 * k + 1] = o2[k][1]; }
;     float r8[8], r4[4], r2[2];
; #pragma unroll
;     for (int k = 0; k < 8; ++k) {
;       const float keep = (lane & 32) ? o[k + 8] : o[k], send = (lane & 32) ? o[k] : o[k + 8];
;       r8[k] = keep + __shfl_xor(send, 32);
;     }
; #pragma unroll
;     for (int k = 0; k < 4; ++k) {
;       const float keep = (lane & 16) ? r8[k + 4] : r8[k], send = (lane & 16) ? r8[k] : r8[k + 4];
;       r4[k] = keep + __shfl_xor(send, 16);
;     }
; #pragma unroll
;     for (int k = 0; k < 2; ++k) {
;       const float keep = (lane & 8) ? r4[k + 2] : r4[k], send = (lane & 8) ? r4[k] : r4[k + 2];
;       r2[k] = keep + __shfl_xor(send, 8);
;     }
;     float* xr = p.out + (size_t)tok * 1024 + 128 * g + 16 * s + 2 * q;
;     float2 y = *(const float2*)xr;
;     y.x += r2[0]; y.y += r2[1];
;     *(float2*)xr = y;
;     const float ss = wave_sum(y.x * y.x + y.y * y.y);
;     if (lane == 0) SSP[tok] = ss;
	v_cvt_pk_f32_fp8_sdwa v[106:107], v92 src0_sel:WORD_1
	v_pk_fma_f32 v[104:105], v[104:105], v[72:73], v[112:113] op_sel_hi:[1,0,1]
	v_pk_fma_f32 v[112:113], v[130:131], v[72:73], v[128:129] op_sel_hi:[1,0,1]
	v_mov_b32_e32 v72, v73
	v_pk_fma_f32 v[122:123], v[126:127], v[72:73], v[122:123] op_sel_hi:[1,0,1]
	v_cvt_pk_f32_fp8_e32 v[126:127], v93
	v_cvt_pk_f32_fp8_sdwa v[92:93], v93 src0_sel:WORD_1
	v_pk_fma_f32 v[106:107], v[106:107], v[72:73], v[114:115] op_sel_hi:[1,0,1]
	v_cvt_pk_f32_fp8_e32 v[114:115], v94
	v_pk_fma_f32 v[124:125], v[126:127], v[72:73], v[124:125] op_sel_hi:[1,0,1]
	v_pk_fma_f32 v[92:93], v[92:93], v[72:73], v[100:101] op_sel_hi:[1,0,1]
	v_cvt_pk_f32_fp8_sdwa v[100:101], v94 src0_sel:WORD_1
	v_pk_fma_f32 v[114:115], v[114:115], v[72:73], v[120:121] op_sel_hi:[1,0,1]
	v_cvt_pk_f32_fp8_e32 v[120:121], v95
	v_cvt_pk_f32_fp8_sdwa v[94:95], v95 src0_sel:WORD_1
	v_pk_fma_f32 v[100:101], v[100:101], v[72:73], v[104:105] op_sel_hi:[1,0,1]
	v_cvt_pk_f32_fp8_e32 v[104:105], v68
	v_pk_fma_f32 v[112:113], v[120:121], v[72:73], v[112:113] op_sel_hi:[1,0,1]
	v_pk_fma_f32 v[72:73], v[94:95], v[72:73], v[102:103] op_sel_hi:[1,0,1]
	v_pk_fma_f32 v[102:103], v[104:105], v[74:75], v[122:123] op_sel_hi:[1,0,1]
	v_cvt_pk_f32_fp8_sdwa v[94:95], v68 src0_sel:WORD_1
	v_cvt_pk_f32_fp8_e32 v[104:105], v69
	v_cvt_pk_f32_fp8_sdwa v[68:69], v69 src0_sel:WORD_1
	v_pk_fma_f32 v[94:95], v[94:95], v[74:75], v[106:107] op_sel_hi:[1,0,1]
	v_pk_fma_f32 v[104:105], v[104:105], v[74:75], v[124:125] op_sel_hi:[1,0,1]
	v_pk_fma_f32 v[68:69], v[68:69], v[74:75], v[92:93] op_sel_hi:[1,0,1]
	v_cvt_pk_f32_fp8_e32 v[92:93], v70
	v_cvt_pk_f32_fp8_sdwa v[106:107], v70 src0_sel:WORD_1
	v_cvt_pk_f32_fp8_e32 v[124:125], v71
	v_cvt_pk_f32_fp8_sdwa v[70:71], v71 src0_sel:WORD_1
	v_pk_fma_f32 v[92:93], v[92:93], v[74:75], v[114:115] op_sel_hi:[1,0,1]
	v_pk_fma_f32 v[100:101], v[106:107], v[74:75], v[100:101] op_sel_hi:[1,0,1]
	v_pk_fma_f32 v[106:107], v[124:125], v[74:75], v[112:113] op_sel_hi:[1,0,1]
	v_pk_fma_f32 v[70:71], v[70:71], v[74:75], v[72:73] op_sel_hi:[1,0,1]
	v_mov_b32_e32 v72, v75
	v_cvt_pk_f32_fp8_e32 v[74:75], v60
	v_cvt_pk_f32_fp8_sdwa v[112:113], v60 src0_sel:WORD_1
	v_cvt_pk_f32_fp8_e32 v[114:115], v61
	v_cvt_pk_f32_fp8_sdwa v[60:61], v61 src0_sel:WORD_1
	v_pk_fma_f32 v[74:75], v[74:75], v[72:73], v[102:103] op_sel_hi:[1,0,1]
	v_pk_fma_f32 v[94:95], v[112:113], v[72:73], v[94:95] op_sel_hi:[1,0,1]
	v_pk_fma_f32 v[102:103], v[114:115], v[72:73], v[104:105] op_sel_hi:[1,0,1]
	v_pk_fma_f32 v[60:61], v[60:61], v[72:73], v[68:69] op_sel_hi:[1,0,1]
	v_cvt_pk_f32_fp8_e32 v[68:69], v62
	v_cvt_pk_f32_fp8_sdwa v[104:105], v62 src0_sel:WORD_1
	v_cvt_pk_f32_fp8_e32 v[112:113], v63
	v_cvt_pk_f32_fp8_sdwa v[62:63], v63 src0_sel:WORD_1
	v_pk_fma_f32 v[68:69], v[68:69], v[72:73], v[92:93] op_sel_hi:[1,0,1]
	v_pk_fma_f32 v[92:93], v[104:105], v[72:73], v[100:101] op_sel_hi:[1,0,1]
	v_pk_fma_f32 v[100:101], v[112:113], v[72:73], v[106:107] op_sel_hi:[1,0,1]
	v_pk_fma_f32 v[62:63], v[62:63], v[72:73], v[70:71] op_sel_hi:[1,0,1]
	v_cndmask_b32_e32 v70, v74, v68, vcc
	v_cndmask_b32_e32 v71, v75, v69, vcc
	ds_bpermute_b32 v70, v210, v70
	ds_bpermute_b32 v71, v210, v71
	v_cndmask_b32_e32 v72, v94, v92, vcc
	v_cndmask_b32_e32 v73, v95, v93, vcc
	ds_bpermute_b32 v72, v210, v72
	ds_bpermute_b32 v73, v210, v73
	v_cndmask_b32_e32 v104, v102, v100, vcc
	v_cndmask_b32_e32 v105, v103, v101, vcc
	v_cndmask_b32_e32 v106, v60, v62, vcc
	v_cndmask_b32_e32 v107, v61, v63, vcc
	ds_bpermute_b32 v104, v210, v104
	ds_bpermute_b32 v105, v210, v105
	ds_bpermute_b32 v106, v210, v106
	ds_bpermute_b32 v107, v210, v107
	v_cndmask_b32_e32 v69, v69, v75, vcc
	v_cndmask_b32_e32 v68, v68, v74, vcc
	s_waitcnt lgkmcnt(6)
	v_pk_add_f32 v[68:69], v[68:69], v[70:71]
	v_cndmask_b32_e32 v71, v93, v95, vcc
	v_cndmask_b32_e32 v70, v92, v94, vcc
	s_waitcnt lgkmcnt(4)
	v_pk_add_f32 v[70:71], v[70:71], v[72:73]
	v_cndmask_b32_e32 v73, v101, v103, vcc
	v_cndmask_b32_e32 v72, v100, v102, vcc
	v_cndmask_b32_e32 v61, v63, v61, vcc
	v_cndmask_b32_e32 v60, v62, v60, vcc
	s_waitcnt lgkmcnt(2)
	v_pk_add_f32 v[72:73], v[72:73], v[104:105]
	s_waitcnt lgkmcnt(0)
	v_pk_add_f32 v[60:61], v[60:61], v[106:107]
	v_cndmask_b32_e64 v75, v73, v69, s[2:3]
	v_cndmask_b32_e64 v63, v69, v73, s[2:3]
	v_cndmask_b32_e64 v69, v70, v60, s[2:3]
	v_cndmask_b32_e64 v62, v68, v72, s[2:3]
	ds_bpermute_b32 v92, v211, v69
	v_cndmask_b32_e64 v69, v71, v61, s[2:3]
	ds_bpermute_b32 v62, v211, v62
	ds_bpermute_b32 v63, v211, v63
	ds_bpermute_b32 v93, v211, v69
	v_cndmask_b32_e64 v74, v72, v68, s[2:3]
	v_cndmask_b32_e64 v61, v61, v71, s[2:3]
	v_cndmask_b32_e64 v60, v60, v70, s[2:3]
	s_waitcnt lgkmcnt(1)
	v_pk_add_f32 v[62:63], v[74:75], v[62:63]
	s_waitcnt lgkmcnt(0)
	v_pk_add_f32 v[60:61], v[60:61], v[92:93]
	s_nop 0
	v_cndmask_b32_e64 v68, v62, v60, s[4:5]
	v_cndmask_b32_e64 v69, v63, v61, s[4:5]
	ds_bpermute_b32 v68, v212, v68
	ds_bpermute_b32 v69, v212, v69
	v_cndmask_b32_e64 v61, v61, v63, s[4:5]
	v_cndmask_b32_e64 v60, v60, v62, s[4:5]
	s_waitcnt lgkmcnt(0)
	v_pk_add_f32 v[60:61], v[60:61], v[68:69]
	s_waitcnt vmcnt(0)
	v_pk_add_f32 v[62:63], v[60:61], v[236:237]
	global_store_dwordx2 v[238:239], v[62:63], off
	v_pk_mul_f32 v[60:61], v[62:63], v[62:63]
	s_nop 0
	v_add_f32_e32 v60, v60, v61
	s_nop 1
	v_add_f32_dpp v60, v60, v60 quad_perm:[1,0,3,2] row_mask:0xf bank_mask:0xf
	s_nop 1
	v_add_f32_dpp v60, v60, v60 quad_perm:[2,3,0,1] row_mask:0xf bank_mask:0xf
	s_nop 1
	v_add_f32_dpp v60, v60, v60 row_half_mirror row_mask:0xf bank_mask:0xf
	s_nop 1
	v_add_f32_dpp v60, v60, v60 row_mirror row_mask:0xf bank_mask:0xf
	s_nop 1
	v_add_f32_dpp v60, v60, v60 row_bcast:15 row_mask:0xa bank_mask:0xf
	s_nop 1
	v_add_f32_dpp v60, v60, v60 row_bcast:31 row_mask:0xc bank_mask:0xf
	s_and_b64 exec, exec, s[6:7]
	s_cbranch_execz .LBB0_1476
	v_mov_b32_e32 v62, v60
	v_lshl_add_u64 v[60:61], v[206:207], 2, s[12:13]
	global_store_dword v[60:61], v62, off
	s_branch .LBB0_1476
